# SGU item: norm-weight loads moved into the item's initial load batch (before stats/barrier), stats vmcnt waits +2
# baseline (speedup 1.0000x reference)
.LBB0_246:
	s_ashr_i32 s3, s2, 31
	s_cmpk_gt_i32 s2, 0x1ff
	s_mov_b64 s[6:7], -1
	s_cbranch_scc0 .LBB0_252
	s_lshl_b32 s6, s2, 3
	s_and_b32 s6, s6, 56
	s_bfe_u32 s7, s2, 0x30005
	s_or_b32 s6, s6, s7
	s_add_i32 s8, s2, 0xfffffe00
	s_lshl_b32 s6, s6, 2
	s_and_b32 s7, s8, 0xffffff00
	s_or_b32 s6, s6, s7
	s_bfe_u32 s7, s2, 0x20003
	s_or_b32 s9, s6, s7
	s_cmpk_lt_u32 s2, 0x400
	v_readlane_b32 s10, v253, 8
	s_cselect_b64 s[6:7], -1, 0
	v_readlane_b32 s11, v253, 9
	s_and_b64 s[6:7], s[10:11], s[6:7]
	s_and_b64 s[6:7], s[6:7], exec
	s_cselect_b32 s10, s9, s8
	s_waitcnt vmcnt(0)
	v_mov_b32_e32 v68, v208
	s_lshl_b32 s6, s10, 5
	s_load_dwordx2 s[8:9], s[0:1], 0xa8
	s_load_dwordx2 s[98:99], s[0:1], 0xa0
	s_and_b32 s14, s10, 3
	s_and_b32 s11, s6, 0x7f80
	v_readlane_b32 s6, v255, 36
	s_or_b32 s6, s14, s6
	s_ashr_i32 s7, s6, 31
	s_lshl_b64 s[12:13], s[6:7], 16
	v_lshlrev_b32_e32 v0, 3, v68
	s_waitcnt lgkmcnt(0)
	s_add_u32 s8, s8, s12
	v_and_b32_e32 v73, 0x78, v0
	v_ashrrev_i32_e32 v74, 4, v68
	s_addc_u32 s9, s9, s13
	v_lshlrev_b32_e32 v0, 2, v73
	v_lshlrev_b32_e32 v4, 7, v74
	v_lshl_add_u64 v[2:3], s[8:9], 0, v[0:1]
	v_ashrrev_i32_e32 v5, 31, v4
	v_lshl_add_u64 v[4:5], v[4:5], 2, v[2:3]
	global_load_dwordx4 v[18:21], v[4:5], off offset:16
	global_load_dwordx4 v[22:25], v[4:5], off
	v_add_u32_e32 v4, s11, v74
	v_ashrrev_i32_e32 v5, 31, v4
	v_readlane_b32 s8, v255, 41
	v_lshlrev_b64 v[4:5], 11, v[4:5]
	v_readlane_b32 s9, v255, 42
	s_lshl_b32 s20, s14, 8
	v_lshlrev_b32_e32 v50, 1, v73
	v_lshl_add_u64 v[4:5], s[8:9], 0, v[4:5]
	v_lshl_add_u64 v[4:5], v[4:5], 0, s[20:21]
	v_mov_b32_e32 v51, v1
	v_lshl_add_u64 v[4:5], v[4:5], 0, v[50:51]
	global_load_dwordx4 v[14:17], v[4:5], off offset:1024
	v_add_u32_e32 v4, 0x200, v68
	v_ashrrev_i32_e32 v71, 4, v4
	v_lshlrev_b32_e32 v4, 7, v71
	v_ashrrev_i32_e32 v5, 31, v4
	v_lshl_add_u64 v[4:5], v[4:5], 2, v[2:3]
	global_load_dwordx4 v[26:29], v[4:5], off offset:16
	global_load_dwordx4 v[30:33], v[4:5], off
	v_add_u32_e32 v4, s11, v71
	v_ashrrev_i32_e32 v5, 31, v4
	v_lshlrev_b64 v[4:5], 11, v[4:5]
	v_lshl_add_u64 v[4:5], s[8:9], 0, v[4:5]
	v_lshl_add_u64 v[4:5], v[4:5], 0, s[20:21]
	v_lshl_add_u64 v[4:5], v[4:5], 0, v[50:51]
	global_load_dwordx4 v[10:13], v[4:5], off offset:1024
	v_add_u32_e32 v4, 0x400, v68
	v_ashrrev_i32_e32 v70, 4, v4
	v_lshlrev_b32_e32 v4, 7, v70
	v_ashrrev_i32_e32 v5, 31, v4
	v_lshl_add_u64 v[4:5], v[4:5], 2, v[2:3]
	global_load_dwordx4 v[34:37], v[4:5], off offset:16
	global_load_dwordx4 v[38:41], v[4:5], off
	v_add_u32_e32 v4, s11, v70
	v_ashrrev_i32_e32 v5, 31, v4
	v_lshlrev_b64 v[4:5], 11, v[4:5]
	v_lshl_add_u64 v[4:5], s[8:9], 0, v[4:5]
	v_lshl_add_u64 v[4:5], v[4:5], 0, s[20:21]
	v_lshl_add_u64 v[4:5], v[4:5], 0, v[50:51]
	global_load_dwordx4 v[6:9], v[4:5], off offset:1024
	v_add_u32_e32 v4, 0x600, v68
	v_ashrrev_i32_e32 v69, 4, v4
	v_lshlrev_b32_e32 v4, 7, v69
	v_ashrrev_i32_e32 v5, 31, v4
	v_lshl_add_u64 v[2:3], v[4:5], 2, v[2:3]
	global_load_dwordx4 v[42:45], v[2:3], off offset:16
	global_load_dwordx4 v[46:49], v[2:3], off
	v_add_u32_e32 v2, s11, v69
	v_ashrrev_i32_e32 v3, 31, v2
	v_lshlrev_b64 v[2:3], 11, v[2:3]
	v_lshl_add_u64 v[2:3], s[8:9], 0, v[2:3]
	v_lshl_add_u64 v[2:3], v[2:3], 0, s[20:21]
	v_ashrrev_i32_e32 v72, 2, v68
	v_lshl_add_u64 v[2:3], v[2:3], 0, v[50:51]
	v_add_u32_e32 v50, s11, v72
	v_ashrrev_i32_e32 v51, 31, v50
	v_and_b32_e32 v75, 3, v68
	v_lshlrev_b64 v[50:51], 11, v[50:51]
	v_lshl_add_u64 v[50:51], s[8:9], 0, v[50:51]
	v_lshlrev_b32_e32 v52, 8, v75
	v_mov_b32_e32 v53, v1
	v_lshl_add_u64 v[66:67], v[50:51], 0, v[52:53]
	global_load_dwordx4 v[2:5], v[2:3], off offset:1024
	s_nop 0
	global_load_dwordx4 v[80:83], v[66:67], off offset:1072
	global_load_dwordx4 v[84:87], v[66:67], off offset:1056
	global_load_dwordx4 v[88:91], v[66:67], off offset:1040
	global_load_dwordx4 v[92:95], v[66:67], off offset:1024
	global_load_dwordx4 v[96:99], v[66:67], off offset:1136
	global_load_dwordx4 v[100:103], v[66:67], off offset:1120
	global_load_dwordx4 v[104:107], v[66:67], off offset:1104
	global_load_dwordx4 v[108:111], v[66:67], off offset:1088
	global_load_dwordx4 v[112:115], v[66:67], off offset:1200
	global_load_dwordx4 v[116:119], v[66:67], off offset:1184
	global_load_dwordx4 v[120:123], v[66:67], off offset:1168
	global_load_dwordx4 v[124:127], v[66:67], off offset:1152
	global_load_dwordx4 v[128:131], v[66:67], off offset:1264
	global_load_dwordx4 v[132:135], v[66:67], off offset:1248
	global_load_dwordx4 v[136:139], v[66:67], off offset:1232
	global_load_dwordx4 v[140:143], v[66:67], off offset:1216
	v_cmp_lt_i32_e32 vcc, v221, v220
	s_lshl_b32 s7, s14, 7
	v_readlane_b32 s100, v255, 38
	v_readlane_b32 s101, v255, 39
	s_lshl_b64 s[100:101], s[100:101], 2
	s_waitcnt lgkmcnt(0)
	s_add_u32 s98, s98, s100
	s_addc_u32 s99, s99, s101
	s_lshl_b32 s100, s7, 2
	s_add_u32 s98, s98, s100
	s_addc_u32 s99, s99, 0
	global_load_dwordx4 v[168:171], v0, s[98:99]
	global_load_dwordx4 v[172:175], v0, s[98:99] offset:16
	s_nop 0
	s_nop 0
	s_nop 0
	s_waitcnt vmcnt(14)
	v_lshlrev_b32_e32 v76, 16, v92
	v_and_b32_e32 v92, 0xffff0000, v92
	v_add_f32_e32 v77, v76, v92
	v_mul_f32_e32 v92, v92, v92
	v_fmac_f32_e32 v92, v76, v76
	v_lshlrev_b32_e32 v76, 16, v93
	v_and_b32_e32 v93, 0xffff0000, v93
	v_add_f32_e32 v78, v76, v93
	v_mul_f32_e32 v93, v93, v93
	v_fmac_f32_e32 v93, v76, v76
	v_add_f32_e32 v92, v92, v93
	v_lshlrev_b32_e32 v93, 16, v94
	v_and_b32_e32 v94, 0xffff0000, v94
	v_add_f32_e32 v76, v93, v94
	v_mul_f32_e32 v94, v94, v94
	v_fmac_f32_e32 v94, v93, v93
	v_add_f32_e32 v92, v94, v92
	v_lshlrev_b32_e32 v93, 16, v95
	v_and_b32_e32 v94, 0xffff0000, v95
	v_add_f32_e32 v95, v93, v94
	v_mul_f32_e32 v94, v94, v94
	v_fmac_f32_e32 v94, v93, v93
	v_lshlrev_b32_e32 v93, 16, v88
	v_and_b32_e32 v88, 0xffff0000, v88
	v_add_f32_e32 v92, v94, v92
	v_add_f32_e32 v94, v93, v88
	v_mul_f32_e32 v88, v88, v88
	v_fmac_f32_e32 v88, v93, v93
	v_add_f32_e32 v88, v88, v92
	v_lshlrev_b32_e32 v92, 16, v89
	v_and_b32_e32 v89, 0xffff0000, v89
	v_add_f32_e32 v93, v92, v89
	v_mul_f32_e32 v89, v89, v89
	v_fmac_f32_e32 v89, v92, v92
	v_add_f32_e32 v88, v89, v88
	v_lshlrev_b32_e32 v89, 16, v90
	v_and_b32_e32 v90, 0xffff0000, v90
	v_add_f32_e32 v92, v89, v90
	v_mul_f32_e32 v90, v90, v90
	v_fmac_f32_e32 v90, v89, v89
	v_add_f32_e32 v88, v90, v88
	v_lshlrev_b32_e32 v89, 16, v91
	v_and_b32_e32 v90, 0xffff0000, v91
	v_add_f32_e32 v91, v89, v90
	v_mul_f32_e32 v90, v90, v90
	v_fmac_f32_e32 v90, v89, v89
	v_lshlrev_b32_e32 v89, 16, v84
	v_and_b32_e32 v84, 0xffff0000, v84
	v_add_f32_e32 v88, v90, v88
	v_add_f32_e32 v90, v89, v84
	v_mul_f32_e32 v84, v84, v84
	v_fmac_f32_e32 v84, v89, v89
	v_add_f32_e32 v84, v84, v88
	v_lshlrev_b32_e32 v88, 16, v85
	v_and_b32_e32 v85, 0xffff0000, v85
	v_add_f32_e32 v89, v88, v85
	v_mul_f32_e32 v85, v85, v85
	v_fmac_f32_e32 v85, v88, v88
	v_add_f32_e32 v84, v85, v84
	v_lshlrev_b32_e32 v85, 16, v86
	v_and_b32_e32 v86, 0xffff0000, v86
	v_add_f32_e32 v88, v85, v86
	v_mul_f32_e32 v86, v86, v86
	v_add_f32_e32 v77, 0, v77
	v_fmac_f32_e32 v86, v85, v85
	v_add_f32_e32 v77, v78, v77
	v_add_f32_e32 v84, v86, v84
	v_lshlrev_b32_e32 v85, 16, v87
	v_and_b32_e32 v86, 0xffff0000, v87
	v_add_f32_e32 v76, v76, v77
	v_add_f32_e32 v87, v85, v86
	v_mul_f32_e32 v86, v86, v86
	v_add_f32_e32 v95, v95, v76
	v_fmac_f32_e32 v86, v85, v85
	v_lshlrev_b32_e32 v85, 16, v80
	v_and_b32_e32 v80, 0xffff0000, v80
	v_add_f32_e32 v94, v94, v95
	v_add_f32_e32 v84, v86, v84
	v_add_f32_e32 v86, v85, v80
	v_mul_f32_e32 v80, v80, v80
	v_add_f32_e32 v93, v93, v94
	v_fmac_f32_e32 v80, v85, v85
	v_add_f32_e32 v92, v92, v93
	v_add_f32_e32 v80, v80, v84
	v_lshlrev_b32_e32 v84, 16, v81
	v_and_b32_e32 v81, 0xffff0000, v81
	v_add_f32_e32 v91, v91, v92
	v_add_f32_e32 v85, v84, v81
	v_mul_f32_e32 v81, v81, v81
	v_add_f32_e32 v90, v90, v91
	v_fmac_f32_e32 v81, v84, v84
	v_add_f32_e32 v89, v89, v90
	v_add_f32_e32 v80, v81, v80
	v_lshlrev_b32_e32 v81, 16, v82
	v_and_b32_e32 v82, 0xffff0000, v82
	v_add_f32_e32 v88, v88, v89
	v_add_f32_e32 v84, v81, v82
	v_mul_f32_e32 v82, v82, v82
	v_add_f32_e32 v87, v87, v88
	v_fmac_f32_e32 v82, v81, v81
	v_add_f32_e32 v86, v86, v87
	v_add_f32_e32 v80, v82, v80
	v_lshlrev_b32_e32 v81, 16, v83
	v_and_b32_e32 v82, 0xffff0000, v83
	v_add_f32_e32 v85, v85, v86
	v_add_f32_e32 v83, v81, v82
	v_mul_f32_e32 v82, v82, v82
	v_add_f32_e32 v84, v84, v85
	v_fmac_f32_e32 v82, v81, v81
	v_add_f32_e32 v77, v83, v84
	v_add_f32_e32 v76, v82, v80
	s_waitcnt vmcnt(10)
	v_lshlrev_b32_e32 v78, 16, v108
	v_and_b32_e32 v108, 0xffff0000, v108
	v_add_f32_e32 v79, v78, v108
	v_mul_f32_e32 v108, v108, v108
	v_fmac_f32_e32 v108, v78, v78
	v_add_f32_e32 v108, v108, v76
	v_lshlrev_b32_e32 v76, 16, v109
	v_and_b32_e32 v109, 0xffff0000, v109
	v_add_f32_e32 v78, v76, v109
	v_mul_f32_e32 v109, v109, v109
	v_fmac_f32_e32 v109, v76, v76
	v_add_f32_e32 v108, v109, v108
	v_lshlrev_b32_e32 v109, 16, v110
	v_and_b32_e32 v110, 0xffff0000, v110
	v_add_f32_e32 v76, v109, v110
	v_mul_f32_e32 v110, v110, v110
	v_fmac_f32_e32 v110, v109, v109
	v_add_f32_e32 v108, v110, v108
	v_lshlrev_b32_e32 v109, 16, v111
	v_and_b32_e32 v110, 0xffff0000, v111
	v_add_f32_e32 v111, v109, v110
	v_mul_f32_e32 v110, v110, v110
	v_fmac_f32_e32 v110, v109, v109
	v_lshlrev_b32_e32 v109, 16, v104
	v_and_b32_e32 v104, 0xffff0000, v104
	v_add_f32_e32 v108, v110, v108
	v_add_f32_e32 v110, v109, v104
	v_mul_f32_e32 v104, v104, v104
	v_fmac_f32_e32 v104, v109, v109
	v_add_f32_e32 v104, v104, v108
	v_lshlrev_b32_e32 v108, 16, v105
	v_and_b32_e32 v105, 0xffff0000, v105
	v_add_f32_e32 v109, v108, v105
	v_mul_f32_e32 v105, v105, v105
	v_fmac_f32_e32 v105, v108, v108
	v_add_f32_e32 v104, v105, v104
	v_lshlrev_b32_e32 v105, 16, v106
	v_and_b32_e32 v106, 0xffff0000, v106
	v_add_f32_e32 v108, v105, v106
	v_mul_f32_e32 v106, v106, v106
	v_fmac_f32_e32 v106, v105, v105
	v_add_f32_e32 v104, v106, v104
	v_lshlrev_b32_e32 v105, 16, v107
	v_and_b32_e32 v106, 0xffff0000, v107
	v_add_f32_e32 v107, v105, v106
	v_mul_f32_e32 v106, v106, v106
	v_fmac_f32_e32 v106, v105, v105
	v_lshlrev_b32_e32 v105, 16, v100
	v_and_b32_e32 v100, 0xffff0000, v100
	v_add_f32_e32 v104, v106, v104
	v_add_f32_e32 v106, v105, v100
	v_mul_f32_e32 v100, v100, v100
	v_fmac_f32_e32 v100, v105, v105
	v_add_f32_e32 v100, v100, v104
	v_lshlrev_b32_e32 v104, 16, v101
	v_and_b32_e32 v101, 0xffff0000, v101
	v_add_f32_e32 v105, v104, v101
	v_mul_f32_e32 v101, v101, v101
	v_fmac_f32_e32 v101, v104, v104
	v_add_f32_e32 v100, v101, v100
	v_lshlrev_b32_e32 v101, 16, v102
	v_and_b32_e32 v102, 0xffff0000, v102
	v_add_f32_e32 v104, v101, v102
	v_mul_f32_e32 v102, v102, v102
	v_add_f32_e32 v77, v79, v77
	v_fmac_f32_e32 v102, v101, v101
	v_add_f32_e32 v77, v78, v77
	v_add_f32_e32 v100, v102, v100
	v_lshlrev_b32_e32 v101, 16, v103
	v_and_b32_e32 v102, 0xffff0000, v103
	v_add_f32_e32 v76, v76, v77
	v_add_f32_e32 v103, v101, v102
	v_mul_f32_e32 v102, v102, v102
	v_add_f32_e32 v111, v111, v76
	v_fmac_f32_e32 v102, v101, v101
	v_lshlrev_b32_e32 v101, 16, v96
	v_and_b32_e32 v96, 0xffff0000, v96
	v_add_f32_e32 v110, v110, v111
	v_add_f32_e32 v100, v102, v100
	v_add_f32_e32 v102, v101, v96
	v_mul_f32_e32 v96, v96, v96
	v_add_f32_e32 v109, v109, v110
	v_fmac_f32_e32 v96, v101, v101
	v_add_f32_e32 v108, v108, v109
	v_add_f32_e32 v96, v96, v100
	v_lshlrev_b32_e32 v100, 16, v97
	v_and_b32_e32 v97, 0xffff0000, v97
	v_add_f32_e32 v107, v107, v108
	v_add_f32_e32 v101, v100, v97
	v_mul_f32_e32 v97, v97, v97
	v_add_f32_e32 v106, v106, v107
	v_fmac_f32_e32 v97, v100, v100
	v_add_f32_e32 v105, v105, v106
	v_add_f32_e32 v96, v97, v96
	v_lshlrev_b32_e32 v97, 16, v98
	v_and_b32_e32 v98, 0xffff0000, v98
	v_add_f32_e32 v104, v104, v105
	v_add_f32_e32 v100, v97, v98
	v_mul_f32_e32 v98, v98, v98
	v_add_f32_e32 v103, v103, v104
	v_fmac_f32_e32 v98, v97, v97
	v_add_f32_e32 v102, v102, v103
	v_add_f32_e32 v96, v98, v96
	v_lshlrev_b32_e32 v97, 16, v99
	v_and_b32_e32 v98, 0xffff0000, v99
	v_add_f32_e32 v101, v101, v102
	v_add_f32_e32 v99, v97, v98
	v_mul_f32_e32 v98, v98, v98
	v_add_f32_e32 v100, v100, v101
	v_fmac_f32_e32 v98, v97, v97
	v_add_f32_e32 v77, v99, v100
	v_add_f32_e32 v76, v98, v96
	s_waitcnt vmcnt(6)
	v_lshlrev_b32_e32 v78, 16, v124
	v_and_b32_e32 v124, 0xffff0000, v124
	v_add_f32_e32 v79, v78, v124
	v_mul_f32_e32 v124, v124, v124
	v_fmac_f32_e32 v124, v78, v78
	v_add_f32_e32 v124, v124, v76
	v_lshlrev_b32_e32 v76, 16, v125
	v_and_b32_e32 v125, 0xffff0000, v125
	v_add_f32_e32 v78, v76, v125
	v_mul_f32_e32 v125, v125, v125
	v_fmac_f32_e32 v125, v76, v76
	v_add_f32_e32 v124, v125, v124
	v_lshlrev_b32_e32 v125, 16, v126
	v_and_b32_e32 v126, 0xffff0000, v126
	v_add_f32_e32 v76, v125, v126
	v_mul_f32_e32 v126, v126, v126
	v_fmac_f32_e32 v126, v125, v125
	v_add_f32_e32 v124, v126, v124
	v_lshlrev_b32_e32 v125, 16, v127
	v_and_b32_e32 v126, 0xffff0000, v127
	v_add_f32_e32 v127, v125, v126
	v_mul_f32_e32 v126, v126, v126
	v_fmac_f32_e32 v126, v125, v125
	v_lshlrev_b32_e32 v125, 16, v120
	v_and_b32_e32 v120, 0xffff0000, v120
	v_add_f32_e32 v124, v126, v124
	v_add_f32_e32 v126, v125, v120
	v_mul_f32_e32 v120, v120, v120
	v_fmac_f32_e32 v120, v125, v125
	v_add_f32_e32 v120, v120, v124
	v_lshlrev_b32_e32 v124, 16, v121
	v_and_b32_e32 v121, 0xffff0000, v121
	v_add_f32_e32 v125, v124, v121
	v_mul_f32_e32 v121, v121, v121
	v_fmac_f32_e32 v121, v124, v124
	v_add_f32_e32 v120, v121, v120
	v_lshlrev_b32_e32 v121, 16, v122
	v_and_b32_e32 v122, 0xffff0000, v122
	v_add_f32_e32 v124, v121, v122
	v_mul_f32_e32 v122, v122, v122
	v_fmac_f32_e32 v122, v121, v121
	v_add_f32_e32 v120, v122, v120
	v_lshlrev_b32_e32 v121, 16, v123
	v_and_b32_e32 v122, 0xffff0000, v123
	v_add_f32_e32 v123, v121, v122
	v_mul_f32_e32 v122, v122, v122
	v_fmac_f32_e32 v122, v121, v121
	v_lshlrev_b32_e32 v121, 16, v116
	v_and_b32_e32 v116, 0xffff0000, v116
	v_add_f32_e32 v120, v122, v120
	v_add_f32_e32 v122, v121, v116
	v_mul_f32_e32 v116, v116, v116
	v_fmac_f32_e32 v116, v121, v121
	v_add_f32_e32 v116, v116, v120
	v_lshlrev_b32_e32 v120, 16, v117
	v_and_b32_e32 v117, 0xffff0000, v117
	v_add_f32_e32 v121, v120, v117
	v_mul_f32_e32 v117, v117, v117
	v_fmac_f32_e32 v117, v120, v120
	v_add_f32_e32 v116, v117, v116
	v_lshlrev_b32_e32 v117, 16, v118
	v_and_b32_e32 v118, 0xffff0000, v118
	v_add_f32_e32 v120, v117, v118
	v_mul_f32_e32 v118, v118, v118
	v_add_f32_e32 v77, v79, v77
	v_fmac_f32_e32 v118, v117, v117
	v_add_f32_e32 v77, v78, v77
	v_add_f32_e32 v116, v118, v116
	v_lshlrev_b32_e32 v117, 16, v119
	v_and_b32_e32 v118, 0xffff0000, v119
	v_add_f32_e32 v76, v76, v77
	v_add_f32_e32 v119, v117, v118
	v_mul_f32_e32 v118, v118, v118
	v_add_f32_e32 v127, v127, v76
	v_fmac_f32_e32 v118, v117, v117
	v_lshlrev_b32_e32 v117, 16, v112
	v_and_b32_e32 v112, 0xffff0000, v112
	v_add_f32_e32 v126, v126, v127
	v_add_f32_e32 v116, v118, v116
	v_add_f32_e32 v118, v117, v112
	v_mul_f32_e32 v112, v112, v112
	v_add_f32_e32 v125, v125, v126
	v_fmac_f32_e32 v112, v117, v117
	v_add_f32_e32 v124, v124, v125
	v_add_f32_e32 v112, v112, v116
	v_lshlrev_b32_e32 v116, 16, v113
	v_and_b32_e32 v113, 0xffff0000, v113
	v_add_f32_e32 v123, v123, v124
	v_add_f32_e32 v117, v116, v113
	v_mul_f32_e32 v113, v113, v113
	v_add_f32_e32 v122, v122, v123
	v_fmac_f32_e32 v113, v116, v116
	v_add_f32_e32 v121, v121, v122
	v_add_f32_e32 v112, v113, v112
	v_lshlrev_b32_e32 v113, 16, v114
	v_and_b32_e32 v114, 0xffff0000, v114
	v_add_f32_e32 v120, v120, v121
	v_add_f32_e32 v116, v113, v114
	v_mul_f32_e32 v114, v114, v114
	v_add_f32_e32 v119, v119, v120
	v_fmac_f32_e32 v114, v113, v113
	v_add_f32_e32 v118, v118, v119
	v_add_f32_e32 v112, v114, v112
	v_lshlrev_b32_e32 v113, 16, v115
	v_and_b32_e32 v114, 0xffff0000, v115
	v_add_f32_e32 v117, v117, v118
	v_add_f32_e32 v115, v113, v114
	v_mul_f32_e32 v114, v114, v114
	v_add_f32_e32 v116, v116, v117
	v_fmac_f32_e32 v114, v113, v113
	v_add_f32_e32 v77, v115, v116
	v_add_f32_e32 v76, v114, v112
	s_waitcnt vmcnt(2)
	v_lshlrev_b32_e32 v66, 16, v140
	v_and_b32_e32 v140, 0xffff0000, v140
	v_add_f32_e32 v67, v66, v140
	v_mul_f32_e32 v140, v140, v140
	v_fmac_f32_e32 v140, v66, v66
	v_lshlrev_b32_e32 v66, 16, v141
	v_and_b32_e32 v141, 0xffff0000, v141
	v_add_f32_e32 v140, v140, v76
	v_add_f32_e32 v76, v66, v141
	v_mul_f32_e32 v141, v141, v141
	v_fmac_f32_e32 v141, v66, v66
	v_add_f32_e32 v140, v141, v140
	v_lshlrev_b32_e32 v141, 16, v142
	v_and_b32_e32 v142, 0xffff0000, v142
	v_add_f32_e32 v66, v141, v142
	v_mul_f32_e32 v142, v142, v142
	v_fmac_f32_e32 v142, v141, v141
	v_add_f32_e32 v140, v142, v140
	v_lshlrev_b32_e32 v141, 16, v143
	v_and_b32_e32 v142, 0xffff0000, v143
	v_add_f32_e32 v143, v141, v142
	v_mul_f32_e32 v142, v142, v142
	v_fmac_f32_e32 v142, v141, v141
	v_lshlrev_b32_e32 v141, 16, v136
	v_and_b32_e32 v136, 0xffff0000, v136
	v_add_f32_e32 v140, v142, v140
	v_add_f32_e32 v142, v141, v136
	v_mul_f32_e32 v136, v136, v136
	v_fmac_f32_e32 v136, v141, v141
	v_add_f32_e32 v136, v136, v140
	v_lshlrev_b32_e32 v140, 16, v137
	v_and_b32_e32 v137, 0xffff0000, v137
	v_add_f32_e32 v141, v140, v137
	v_mul_f32_e32 v137, v137, v137
	v_fmac_f32_e32 v137, v140, v140
	v_add_f32_e32 v136, v137, v136
	v_lshlrev_b32_e32 v137, 16, v138
	v_and_b32_e32 v138, 0xffff0000, v138
	v_add_f32_e32 v140, v137, v138
	v_mul_f32_e32 v138, v138, v138
	v_fmac_f32_e32 v138, v137, v137
	v_add_f32_e32 v136, v138, v136
	v_lshlrev_b32_e32 v137, 16, v139
	v_and_b32_e32 v138, 0xffff0000, v139
	v_add_f32_e32 v139, v137, v138
	v_mul_f32_e32 v138, v138, v138
	v_fmac_f32_e32 v138, v137, v137
	v_lshlrev_b32_e32 v137, 16, v132
	v_and_b32_e32 v132, 0xffff0000, v132
	v_add_f32_e32 v136, v138, v136
	v_add_f32_e32 v138, v137, v132
	v_mul_f32_e32 v132, v132, v132
	v_fmac_f32_e32 v132, v137, v137
	v_add_f32_e32 v132, v132, v136
	v_lshlrev_b32_e32 v136, 16, v133
	v_and_b32_e32 v133, 0xffff0000, v133
	v_add_f32_e32 v137, v136, v133
	v_mul_f32_e32 v133, v133, v133
	v_fmac_f32_e32 v133, v136, v136
	v_add_f32_e32 v132, v133, v132
	v_lshlrev_b32_e32 v133, 16, v134
	v_and_b32_e32 v134, 0xffff0000, v134
	v_add_f32_e32 v136, v133, v134
	v_mul_f32_e32 v134, v134, v134
	v_fmac_f32_e32 v134, v133, v133
	v_add_f32_e32 v67, v67, v77
	v_add_f32_e32 v132, v134, v132
	v_lshlrev_b32_e32 v133, 16, v135
	v_and_b32_e32 v134, 0xffff0000, v135
	v_add_f32_e32 v67, v76, v67
	v_add_f32_e32 v135, v133, v134
	v_mul_f32_e32 v134, v134, v134
	v_add_f32_e32 v66, v66, v67
	v_fmac_f32_e32 v134, v133, v133
	v_lshlrev_b32_e32 v133, 16, v128
	v_and_b32_e32 v128, 0xffff0000, v128
	v_add_f32_e32 v143, v143, v66
	v_add_f32_e32 v132, v134, v132
	v_add_f32_e32 v134, v133, v128
	v_mul_f32_e32 v128, v128, v128
	v_add_f32_e32 v142, v142, v143
	v_fmac_f32_e32 v128, v133, v133
	v_add_f32_e32 v141, v141, v142
	v_add_f32_e32 v128, v128, v132
	v_lshlrev_b32_e32 v132, 16, v129
	v_and_b32_e32 v129, 0xffff0000, v129
	v_add_f32_e32 v140, v140, v141
	v_add_f32_e32 v133, v132, v129
	v_mul_f32_e32 v129, v129, v129
	v_add_f32_e32 v139, v139, v140
	v_fmac_f32_e32 v129, v132, v132
	v_add_f32_e32 v138, v138, v139
	v_add_f32_e32 v128, v129, v128
	v_lshlrev_b32_e32 v129, 16, v130
	v_and_b32_e32 v130, 0xffff0000, v130
	v_add_f32_e32 v137, v137, v138
	v_add_f32_e32 v132, v129, v130
	v_mul_f32_e32 v130, v130, v130
	v_add_f32_e32 v136, v136, v137
	v_fmac_f32_e32 v130, v129, v129
	v_add_f32_e32 v135, v135, v136
	v_add_f32_e32 v128, v130, v128
	v_lshlrev_b32_e32 v129, 16, v131
	v_and_b32_e32 v130, 0xffff0000, v131
	v_add_f32_e32 v134, v134, v135
	v_add_f32_e32 v131, v129, v130
	v_mul_f32_e32 v130, v130, v130
	v_add_f32_e32 v133, v133, v134
	v_fmac_f32_e32 v130, v129, v129
	v_add_f32_e32 v132, v132, v133
	v_add_f32_e32 v130, v130, v128
	v_cndmask_b32_e32 v128, v218, v221, vcc
	v_add_f32_e32 v131, v131, v132
	v_lshlrev_b32_e32 v132, 2, v128
	ds_bpermute_b32 v128, v132, v131
	ds_bpermute_b32 v132, v132, v130
	v_cmp_lt_i32_e32 vcc, v222, v220
	s_waitcnt lgkmcnt(1)
	v_add_f32_e32 v128, v131, v128
	v_cndmask_b32_e32 v129, v218, v222, vcc
	v_lshlrev_b32_e32 v131, 2, v129
	s_waitcnt lgkmcnt(0)
	v_add_f32_e32 v130, v130, v132
	ds_bpermute_b32 v129, v131, v128
	ds_bpermute_b32 v131, v131, v130
	v_cmp_eq_u32_e32 vcc, 0, v75
	s_and_saveexec_b64 s[8:9], vcc
	s_cbranch_execz .LBB0_249
	s_waitcnt lgkmcnt(1)
	v_add_f32_e32 v128, v128, v129
	v_mul_f32_e32 v128, 0x3b000000, v128
	s_waitcnt lgkmcnt(0)
	v_add_f32_e32 v130, v130, v131
	v_mul_f32_e32 v129, v128, v128
	s_mov_b32 s12, 0x3b000000
	v_fma_f32 v129, v130, s12, -v129
	v_max_f32_e32 v129, 0, v129
	v_add_f32_e32 v129, 0x358637bd, v129
	v_mul_f32_e32 v130, 0x4f800000, v129
	v_cmp_gt_f32_e32 vcc, s23, v129
	s_nop 1
	v_cndmask_b32_e32 v129, v129, v130, vcc
	v_sqrt_f32_e32 v130, v129
	s_nop 0
	v_add_u32_e32 v131, -1, v130
	v_fma_f32 v132, -v131, v130, v129
	v_cmp_ge_f32_e64 s[42:43], 0, v132
	v_add_u32_e32 v132, 1, v130
	s_nop 0
	v_cndmask_b32_e64 v131, v130, v131, s[42:43]
	v_fma_f32 v130, -v132, v130, v129
	v_cmp_lt_f32_e64 s[42:43], 0, v130
	s_nop 1
	v_cndmask_b32_e64 v130, v131, v132, s[42:43]
	v_mul_f32_e32 v131, 0x37800000, v130
	v_cndmask_b32_e32 v130, v130, v131, vcc
	v_cmp_class_f32_e32 vcc, v129, v210
	v_lshl_add_u32 v132, v72, 2, 0
	v_add_u32_e32 v132, 0x20000, v132
	v_cndmask_b32_e32 v129, v130, v129, vcc
	v_div_scale_f32 v130, s[12:13], v129, v129, 1.0
	v_rcp_f32_e32 v131, v130
	s_nop 0
	v_fma_f32 v133, -v130, v131, 1.0
	v_fmac_f32_e32 v131, v133, v131
	v_div_scale_f32 v133, vcc, 1.0, v129, 1.0
	v_mul_f32_e32 v134, v133, v131
	v_fma_f32 v135, -v130, v134, v133
	v_fmac_f32_e32 v134, v135, v131
	v_fma_f32 v130, -v130, v134, v133
	v_div_fmas_f32 v130, v130, v131, v134
	v_div_fixup_f32 v129, v130, v129, 1.0
	ds_write2st64_b32 v132, v128, v129 offset1:2
.LBB0_249:
	s_or_b64 exec, exec, s[8:9]
	v_lshl_add_u32 v50, v73, 1, 0
	s_movk_i32 s14, 0x110
	v_cvt_pk_bf16_f32 v22, v22, v23
	v_cvt_pk_bf16_f32 v23, v24, v25
	v_cvt_pk_bf16_f32 v24, v18, v19
	s_waitcnt lgkmcnt(1)
	v_mad_u64_u32 v[18:19], s[8:9], v74, s14, v[50:51]
	v_cvt_pk_bf16_f32 v25, v20, v21
	ds_write_b128 v18, v[22:25]
	v_mad_u64_u32 v[22:23], s[8:9], v71, s14, v[50:51]
	v_cvt_pk_bf16_f32 v18, v30, v31
	v_cvt_pk_bf16_f32 v19, v32, v33
	v_cvt_pk_bf16_f32 v20, v26, v27
	v_cvt_pk_bf16_f32 v21, v28, v29
	ds_write_b128 v22, v[18:21]
	v_mad_u64_u32 v[22:23], s[8:9], v70, s14, v[50:51]
	v_cvt_pk_bf16_f32 v18, v38, v39
	v_cvt_pk_bf16_f32 v19, v40, v41
	v_cvt_pk_bf16_f32 v20, v34, v35
	v_cvt_pk_bf16_f32 v21, v36, v37
	ds_write_b128 v22, v[18:21]
	v_mad_u64_u32 v[22:23], s[8:9], v69, s14, v[50:51]
	v_cvt_pk_bf16_f32 v18, v46, v47
	v_cvt_pk_bf16_f32 v19, v48, v49
	v_cvt_pk_bf16_f32 v20, v42, v43
	v_cvt_pk_bf16_f32 v21, v44, v45
	ds_write_b128 v22, v[18:21]
	s_waitcnt lgkmcnt(0)
	s_barrier
	s_load_dwordx2 s[8:9], s[0:1], 0xa0
	s_load_dwordx2 s[42:43], s[0:1], 0xb0
	v_readlane_b32 s16, v255, 38
	v_readlane_b32 s17, v255, 39
	s_lshl_b64 s[12:13], s[16:17], 2
	v_and_b32_e32 v26, 0xffff0000, v14
	s_waitcnt lgkmcnt(0)
	s_add_u32 s8, s8, s12
	s_addc_u32 s9, s9, s13
	s_lshl_b32 s12, s7, 2
	s_add_u32 s8, s8, s12
	s_addc_u32 s9, s9, 0
	v_and_b32_e32 v156, 15, v68
	v_bfe_u32 v157, v68, 4, 2
	v_and_b32_e32 v158, -16, v72
	v_lshl_or_b32 v158, v157, 2, v158
	v_ashrrev_i32_e32 v159, 31, v158
	v_mov_b32_e32 v160, s20
	v_mov_b32_e32 v161, 0
	v_lshl_add_u64 v[162:163], v[158:159], 1, v[160:161]
	s_add_i32 s98, s11, 16
	v_add_lshl_u32 v160, s98, v156, 11
	v_lshl_add_u64 v[164:165], v[162:163], 0, v[160:161]
	s_lshl_b32 s98, s10, 16
	s_and_b32 s98, s98, 0x3fc0000
	v_lshl_or_b32 v160, v156, 11, s98
	v_lshl_add_u64 v[162:163], v[162:163], 0, v[160:161]
	v_lshl_add_u64 v[164:165], s[64:65], 0, v[164:165]
	v_lshl_add_u64 v[162:163], s[64:65], 0, v[162:163]
	s_add_i32 s98, s16, s7
	v_add_u32_e32 v166, s98, v156
	v_ashrrev_i32_e32 v167, 31, v166
	v_lshl_add_u64 v[166:167], v[166:167], 2, s[42:43]
	global_load_dword v80, v[166:167], off
	global_load_dword v81, v[166:167], off offset:64
	global_load_dword v82, v[166:167], off offset:128
	global_load_dword v83, v[166:167], off offset:192
	global_load_dword v84, v[166:167], off offset:256
	global_load_dword v85, v[166:167], off offset:320
	global_load_dword v86, v[166:167], off offset:384
	global_load_dword v87, v[166:167], off offset:448
	s_mov_b32 s98, 0xc200000
	s_mov_b32 s99, 0
	v_lshl_add_u64 v[160:161], v[162:163], 0, s[98:99]
	global_load_dwordx2 v[88:89], v[160:161], off
	v_lshl_add_u64 v[160:161], v[164:165], 0, s[98:99]
	global_load_dwordx2 v[90:91], v[160:161], off
	s_add_u32 s98, s98, 0x10000
	v_lshl_add_u64 v[160:161], v[162:163], 0, s[98:99]
	global_load_dwordx2 v[92:93], v[160:161], off
	v_lshl_add_u64 v[160:161], v[164:165], 0, s[98:99]
	global_load_dwordx2 v[94:95], v[160:161], off
	s_add_u32 s98, s98, 0x10000
	v_lshl_add_u64 v[160:161], v[162:163], 0, s[98:99]
	global_load_dwordx2 v[96:97], v[160:161], off
	v_lshl_add_u64 v[160:161], v[164:165], 0, s[98:99]
	global_load_dwordx2 v[98:99], v[160:161], off
	s_add_u32 s98, s98, 0x10000
	v_lshl_add_u64 v[160:161], v[162:163], 0, s[98:99]
	global_load_dwordx2 v[100:101], v[160:161], off
	v_lshl_add_u64 v[160:161], v[164:165], 0, s[98:99]
	global_load_dwordx2 v[102:103], v[160:161], off
	s_nop 0
	s_nop 0
	s_add_i32 s12, 0, 0x20000
	v_lshlrev_b32_e32 v0, 16, v14
	v_lshl_add_u32 v14, v74, 2, s12
	v_lshlrev_b32_e32 v27, 16, v15
	v_and_b32_e32 v28, 0xffff0000, v15
	ds_read2st64_b32 v[14:15], v14 offset1:2
	v_lshlrev_b32_e32 v29, 16, v16
	v_and_b32_e32 v16, 0xffff0000, v16
	v_lshlrev_b32_e32 v30, 16, v17
	v_and_b32_e32 v17, 0xffff0000, v17
	s_waitcnt lgkmcnt(0)
	v_sub_f32_e32 v0, v0, v14
	v_sub_f32_e32 v26, v26, v14
	v_sub_f32_e32 v27, v27, v14
	v_sub_f32_e32 v28, v28, v14
	v_sub_f32_e32 v29, v29, v14
	v_sub_f32_e32 v16, v16, v14
	v_sub_f32_e32 v30, v30, v14
	v_sub_f32_e32 v14, v17, v14
	v_mul_f32_e32 v0, v15, v0
	v_mul_f32_e32 v17, v15, v26
	v_mul_f32_e32 v26, v15, v27
	v_mul_f32_e32 v27, v15, v28
	v_mul_f32_e32 v28, v15, v29
	v_mul_f32_e32 v16, v15, v16
	v_mul_f32_e32 v29, v15, v30
	v_mul_f32_e32 v14, v15, v14
	v_xor_b32_e32 v31, v74, v73
	v_lshlrev_b32_e32 v31, 1, v31
	v_mul_u32_u24_e32 v32, 0x110, v73
	v_add3_u32 v31, 0, v31, v32
	s_load_dwordx2 s[8:9], s[0:1], 0xb0
	s_add_i32 s11, s11, 16
	s_lshl_b32 s6, s6, 7
	s_waitcnt vmcnt(17)
	v_mul_f32_e32 v0, v168, v0
	v_mul_f32_e32 v15, v169, v17
	v_mul_f32_e32 v17, v170, v26
	v_mul_f32_e32 v26, v171, v27
	s_waitcnt vmcnt(16)
	v_mul_f32_e32 v27, v172, v28
	v_mul_f32_e32 v16, v173, v16
	v_mul_f32_e32 v28, v174, v29
	v_mul_f32_e32 v29, v175, v14
	v_bfe_u32 v14, v0, 16, 1
	v_bfe_u32 v30, v15, 16, 1
	v_bfe_u32 v33, v17, 16, 1
	v_bfe_u32 v34, v26, 16, 1
	v_bfe_u32 v35, v27, 16, 1
	v_bfe_u32 v36, v16, 16, 1
	v_add3_u32 v0, v0, v14, s90
	v_add3_u32 v14, v15, v30, s90
	v_add3_u32 v15, v17, v33, s90
	v_add3_u32 v17, v26, v34, s90
	v_add3_u32 v26, v27, v35, s90
	v_add3_u32 v16, v16, v36, s90
	ds_write_b16_d16_hi v31, v0 offset:34816
	ds_write_b16_d16_hi v31, v14 offset:35088
	ds_write_b16_d16_hi v31, v15 offset:35360
	ds_write_b16_d16_hi v31, v17 offset:35632
	ds_write_b16_d16_hi v31, v26 offset:35904
	ds_write_b16_d16_hi v31, v16 offset:36176
	v_bfe_u32 v0, v28, 16, 1
	v_add3_u32 v0, v28, v0, s90
	ds_write_b16_d16_hi v31, v0 offset:36448
	v_lshl_add_u32 v0, v71, 2, s12
	ds_read2st64_b32 v[14:15], v0 offset1:2
	v_bfe_u32 v0, v29, 16, 1
	v_add3_u32 v0, v29, v0, s90
	ds_write_b16_d16_hi v31, v0 offset:36720
	v_lshlrev_b32_e32 v0, 16, v10
	s_waitcnt lgkmcnt(0)
	v_sub_f32_e32 v0, v0, v14
	v_mul_f32_e32 v0, v15, v0
	v_and_b32_e32 v10, 0xffff0000, v10
	v_lshlrev_b32_e32 v16, 16, v11
	v_and_b32_e32 v11, 0xffff0000, v11
	v_lshlrev_b32_e32 v17, 16, v12
	v_and_b32_e32 v12, 0xffff0000, v12
	v_lshlrev_b32_e32 v26, 16, v13
	v_and_b32_e32 v13, 0xffff0000, v13
	v_mul_f32_e32 v0, v168, v0
	v_sub_f32_e32 v10, v10, v14
	v_sub_f32_e32 v16, v16, v14
	v_sub_f32_e32 v11, v11, v14
	v_sub_f32_e32 v17, v17, v14
	v_sub_f32_e32 v12, v12, v14
	v_sub_f32_e32 v26, v26, v14
	v_sub_f32_e32 v13, v13, v14
	v_mul_f32_e32 v10, v15, v10
	v_mul_f32_e32 v16, v15, v16
	v_mul_f32_e32 v11, v15, v11
	v_mul_f32_e32 v17, v15, v17
	v_mul_f32_e32 v12, v15, v12
	v_mul_f32_e32 v26, v15, v26
	v_mul_f32_e32 v13, v15, v13
	v_xor_b32_e32 v14, v71, v73
	v_lshlrev_b32_e32 v14, 1, v14
	v_bfe_u32 v15, v0, 16, 1
	v_mul_f32_e32 v10, v169, v10
	v_add3_u32 v0, v0, v15, s90
	v_add3_u32 v14, 0, v14, v32
	ds_write_b16_d16_hi v14, v0 offset:34816
	v_bfe_u32 v0, v10, 16, 1
	v_mul_f32_e32 v16, v170, v16
	v_add3_u32 v0, v10, v0, s90
	ds_write_b16_d16_hi v14, v0 offset:35088
	v_bfe_u32 v0, v16, 16, 1
	v_mul_f32_e32 v11, v171, v11
	v_add3_u32 v0, v16, v0, s90
	ds_write_b16_d16_hi v14, v0 offset:35360
	v_bfe_u32 v0, v11, 16, 1
	v_mul_f32_e32 v17, v172, v17
	v_add3_u32 v0, v11, v0, s90
	ds_write_b16_d16_hi v14, v0 offset:35632
	v_bfe_u32 v0, v17, 16, 1
	v_mul_f32_e32 v12, v173, v12
	v_add3_u32 v0, v17, v0, s90
	ds_write_b16_d16_hi v14, v0 offset:35904
	v_bfe_u32 v0, v12, 16, 1
	v_mul_f32_e32 v26, v174, v26
	v_add3_u32 v0, v12, v0, s90
	ds_write_b16_d16_hi v14, v0 offset:36176
	v_bfe_u32 v0, v26, 16, 1
	v_add3_u32 v0, v26, v0, s90
	ds_write_b16_d16_hi v14, v0 offset:36448
	v_lshl_add_u32 v0, v70, 2, s12
	ds_read2st64_b32 v[10:11], v0 offset1:2
	v_mul_f32_e32 v13, v175, v13
	v_bfe_u32 v0, v13, 16, 1
	v_add3_u32 v0, v13, v0, s90
	ds_write_b16_d16_hi v14, v0 offset:36720
	v_lshlrev_b32_e32 v0, 16, v6
	s_waitcnt lgkmcnt(1)
	v_sub_f32_e32 v0, v0, v10
	v_mul_f32_e32 v0, v11, v0
	v_and_b32_e32 v6, 0xffff0000, v6
	v_lshlrev_b32_e32 v12, 16, v7
	v_and_b32_e32 v7, 0xffff0000, v7
	v_lshlrev_b32_e32 v13, 16, v8
	v_and_b32_e32 v8, 0xffff0000, v8
	v_lshlrev_b32_e32 v14, 16, v9
	v_and_b32_e32 v9, 0xffff0000, v9
	v_mul_f32_e32 v0, v168, v0
	v_sub_f32_e32 v6, v6, v10
	v_sub_f32_e32 v12, v12, v10
	v_sub_f32_e32 v7, v7, v10
	v_sub_f32_e32 v13, v13, v10
	v_sub_f32_e32 v8, v8, v10
	v_sub_f32_e32 v14, v14, v10
	v_sub_f32_e32 v9, v9, v10
	v_mul_f32_e32 v6, v11, v6
	v_mul_f32_e32 v12, v11, v12
	v_mul_f32_e32 v7, v11, v7
	v_mul_f32_e32 v13, v11, v13
	v_mul_f32_e32 v8, v11, v8
	v_mul_f32_e32 v14, v11, v14
	v_mul_f32_e32 v9, v11, v9
	v_xor_b32_e32 v10, v70, v73
	v_lshlrev_b32_e32 v10, 1, v10
	v_bfe_u32 v11, v0, 16, 1
	v_mul_f32_e32 v6, v169, v6
	v_add3_u32 v0, v0, v11, s90
	v_add3_u32 v10, 0, v10, v32
	ds_write_b16_d16_hi v10, v0 offset:34816
	v_bfe_u32 v0, v6, 16, 1
	v_mul_f32_e32 v12, v170, v12
	v_add3_u32 v0, v6, v0, s90
	ds_write_b16_d16_hi v10, v0 offset:35088
	v_bfe_u32 v0, v12, 16, 1
	v_mul_f32_e32 v7, v171, v7
	v_add3_u32 v0, v12, v0, s90
	ds_write_b16_d16_hi v10, v0 offset:35360
	v_bfe_u32 v0, v7, 16, 1
	v_mul_f32_e32 v13, v172, v13
	v_add3_u32 v0, v7, v0, s90
	ds_write_b16_d16_hi v10, v0 offset:35632
	v_bfe_u32 v0, v13, 16, 1
	v_mul_f32_e32 v8, v173, v8
	v_add3_u32 v0, v13, v0, s90
	ds_write_b16_d16_hi v10, v0 offset:35904
	v_bfe_u32 v0, v8, 16, 1
	v_mul_f32_e32 v14, v174, v14
	v_add3_u32 v0, v8, v0, s90
	ds_write_b16_d16_hi v10, v0 offset:36176
	v_bfe_u32 v0, v14, 16, 1
	v_add3_u32 v0, v14, v0, s90
	ds_write_b16_d16_hi v10, v0 offset:36448
	v_lshl_add_u32 v0, v69, 2, s12
	ds_read2st64_b32 v[6:7], v0 offset1:2
	v_mul_f32_e32 v9, v175, v9
	v_bfe_u32 v0, v9, 16, 1
	v_add3_u32 v0, v9, v0, s90
	ds_write_b16_d16_hi v10, v0 offset:36720
	v_lshlrev_b32_e32 v0, 16, v2
	s_waitcnt lgkmcnt(1)
	v_sub_f32_e32 v0, v0, v6
	v_mul_f32_e32 v0, v7, v0
	v_and_b32_e32 v2, 0xffff0000, v2
	v_lshlrev_b32_e32 v8, 16, v3
	v_and_b32_e32 v3, 0xffff0000, v3
	v_lshlrev_b32_e32 v9, 16, v4
	v_and_b32_e32 v4, 0xffff0000, v4
	v_lshlrev_b32_e32 v10, 16, v5
	v_and_b32_e32 v5, 0xffff0000, v5
	v_mul_f32_e32 v0, v168, v0
	v_sub_f32_e32 v2, v2, v6
	v_sub_f32_e32 v8, v8, v6
	v_sub_f32_e32 v3, v3, v6
	v_sub_f32_e32 v9, v9, v6
	v_sub_f32_e32 v4, v4, v6
	v_sub_f32_e32 v10, v10, v6
	v_sub_f32_e32 v5, v5, v6
	v_mul_f32_e32 v2, v7, v2
	v_mul_f32_e32 v8, v7, v8
	v_mul_f32_e32 v3, v7, v3
	v_mul_f32_e32 v9, v7, v9
	v_mul_f32_e32 v4, v7, v4
	v_mul_f32_e32 v10, v7, v10
	v_mul_f32_e32 v5, v7, v5
	v_xor_b32_e32 v6, v69, v73
	v_lshlrev_b32_e32 v6, 1, v6
	v_bfe_u32 v7, v0, 16, 1
	v_mul_f32_e32 v2, v169, v2
	v_add3_u32 v0, v0, v7, s90
	v_add3_u32 v6, 0, v6, v32
	ds_write_b16_d16_hi v6, v0 offset:34816
	v_bfe_u32 v0, v2, 16, 1
	v_mul_f32_e32 v8, v170, v8
	v_add3_u32 v0, v2, v0, s90
	ds_write_b16_d16_hi v6, v0 offset:35088
	v_bfe_u32 v0, v8, 16, 1
	v_mul_f32_e32 v3, v171, v3
	v_add3_u32 v0, v8, v0, s90
	ds_write_b16_d16_hi v6, v0 offset:35360
	v_bfe_u32 v0, v3, 16, 1
	v_mul_f32_e32 v9, v172, v9
	v_add3_u32 v0, v3, v0, s90
	ds_write_b16_d16_hi v6, v0 offset:35632
	v_bfe_u32 v0, v9, 16, 1
	v_mul_f32_e32 v4, v173, v4
	v_add3_u32 v0, v9, v0, s90
	ds_write_b16_d16_hi v6, v0 offset:35904
	v_bfe_u32 v0, v4, 16, 1
	v_mul_f32_e32 v10, v174, v10
	v_add3_u32 v0, v4, v0, s90
	ds_write_b16_d16_hi v6, v0 offset:36176
	v_bfe_u32 v0, v10, 16, 1
	v_mul_f32_e32 v5, v175, v5
	v_add3_u32 v0, v10, v0, s90
	ds_write_b16_d16_hi v6, v0 offset:36448
	v_bfe_u32 v0, v5, 16, 1
	v_add3_u32 v0, v5, v0, s90
	ds_write_b16_d16_hi v6, v0 offset:36720
	v_bfe_u32 v18, v68, 4, 2
	v_bfi_b32 v0, -16, v72, v68
	v_and_b32_e32 v200, 0x18, v0
	v_lshrrev_b32_e32 v201, 5, v0
	v_lshlrev_b32_e32 v200, 1, v200
	v_and_b32_e32 v201, 3, v201
	v_and_b32_e32 v19, -16, v72
	v_mul_lo_u32 v0, v0, s14
	v_lshlrev_b32_e32 v22, 4, v18
	v_lshlrev_b32_e32 v201, 6, v201
	v_xor_b32_e32 v200, v22, v200
	v_add3_u32 v0, 0, v0, v200
	v_xor_b32_e32 v203, 64, v201
	v_xor_b32_e32 v204, 0x80, v201
	v_xor_b32_e32 v205, 0xc0, v201
	v_add_u32_e32 v202, v0, v201
	v_add_u32_e32 v203, v0, v203
	v_add_u32_e32 v204, v0, v204
	v_add_u32_e32 v205, v0, v205
	v_lshl_or_b32 v18, v18, 2, v19
	s_waitcnt lgkmcnt(0)
	s_barrier
	v_and_b32_e32 v23, 15, v68
	ds_read_b128 v[2:5], v202 offset:34816
	ds_read_b128 v[6:9], v203 offset:34816
	ds_read_b128 v[10:13], v204 offset:34816
	ds_read_b128 v[14:17], v205 offset:34816
	v_mov_b32_e32 v0, s20
	v_ashrrev_i32_e32 v19, 31, v18
	v_lshl_add_u64 v[24:25], v[18:19], 1, v[0:1]
	v_add_lshl_u32 v0, s11, v23, 11
	s_ashr_i32 s12, s6, 31
	v_or_b32_e32 v20, s6, v23
	v_lshl_add_u64 v[18:19], v[24:25], 0, v[0:1]
	v_mul_u32_u24_e32 v0, 0x110, v23
	s_add_i32 s6, s16, s7
	v_add3_u32 v26, v0, v22, 0
	v_add_u32_e32 v22, s6, v23
	s_lshl_b32 s6, s10, 16
	s_and_b32 s6, s6, 0x3fc0000
	v_mov_b32_e32 v21, s12
	v_lshl_or_b32 v0, v23, 11, s6
	v_lshl_add_u64 v[20:21], v[20:21], 2, s[8:9]
	v_lshl_add_u64 v[24:25], v[24:25], 0, v[0:1]
	v_lshl_add_u64 v[18:19], s[64:65], 0, v[18:19]
	v_lshl_add_u64 v[20:21], v[20:21], 0, 64
	v_lshl_add_u64 v[24:25], s[64:65], 0, v[24:25]
	s_mov_b64 s[6:7], 0
